# DN-prep gate: a_log load issued with the other gate loads (one round trip)
# speedup vs baseline: 1.0177x; 1.0032x over previous
; DI float bf2f(bf16_t b) { return __uint_as_float(((unsigned)b) << 16); }
;     ...
;     const int bh = item >> 6, n = item & 63, b = bh >> 2, h = bh & 3;
;     const int t0 = b * SEQ + n * 64, s0 = n * 64;
;     bf16_t* RT = (bf16_t*)smem;
;     float* R1 = (float*)(smem + 36864);
;     bf16_t* qs = (bf16_t*)(smem + 69632);
;     bf16_t* ks = (bf16_t*)(smem + 87040);
;     float* Lm = (float*)(smem + 104448);
;     float* Tm = (float*)(smem + 121856);
;     float* tmp = (float*)(smem + 139264);
;     bf16_t* Tb = (bf16_t*)(smem + 143488);
;     float* gcs = (float*)(smem + 152704); float* betas = gcs + 64; float* egs = gcs + 128;
;     float xr[3][19];
;     { const int seg = tid >> 7, c = tid & 127, tt0 = seg * 16;
; #pragma unroll
;       for (int part = 0; part < 3; ++part) { const bf16_t* src = a.proj + (size_t)t0 * PLD + part * 512 + h * 128 + c;
; #pragma unroll
;           for (int e = 0; e < 19; ++e) { const int ti = tt0 + e - 3; const bool ok = (s0 + ti >= 0); const float vv = bf2f(src[(long)(ok ? ti : 0) * PLD]); xr[part][e] = ok ? vv : 0.f; } } }
.LBB0_397:
	s_lshl_b32 s0, s24, 4
	s_lshl_b32 s1, s24, 6
	s_and_b32 s0, s0, 0xfffff000
	s_and_b32 s1, s1, 0xfc0
	s_or_b32 s0, s0, s1
	s_bfe_u32 s13, s24, 0x20006
	s_mul_i32 s12, s0, 0x2780
	v_mov_b32_e32 v38, v225
	s_mul_hi_i32 s4, s0, 0x2780
	s_add_u32 s12, s30, s12
	s_addc_u32 s4, s31, s4
	v_ashrrev_i32_e32 v39, 3, v38
	s_lshl_b32 s25, s13, 8
	v_and_b32_e32 v19, 0x7f, v38
	v_and_b32_e32 v20, -16, v39
	s_add_u32 s34, s12, s25
	s_addc_u32 s35, s4, 0
	v_lshlrev_b32_e32 v0, 1, v19
	s_not_b32 s1, s1
	v_add_u32_e32 v12, -3, v20
	s_waitcnt vmcnt(0)
	v_lshl_add_u64 v[2:3], s[34:35], 0, v[0:1]
	v_mad_i64_i32 v[10:11], s[34:35], v12, s3, 0
	v_cmp_lt_i32_e64 s[44:45], s1, v12
	v_add_u32_e32 v13, -2, v20
	v_or_b32_e32 v35, 3, v20
	v_cndmask_b32_e64 v11, 0, v11, s[44:45]
	v_cndmask_b32_e64 v10, 0, v10, s[44:45]
	v_lshl_add_u64 v[50:51], v[2:3], 0, v[10:11]
	v_mad_i64_i32 v[10:11], s[34:35], v13, s3, 0
	v_cmp_lt_i32_e64 s[46:47], s1, v13
	v_mad_i64_i32 v[12:13], s[34:35], v35, s3, 0
	v_cmp_lt_i32_e64 s[52:53], s1, v35
	v_or_b32_e32 v33, 4, v20
	v_cmp_lt_i32_e64 s[54:55], s1, v33
	v_cndmask_b32_e64 v13, 0, v13, s[52:53]
	v_cndmask_b32_e64 v12, 0, v12, s[52:53]
	v_lshl_add_u64 v[16:17], v[2:3], 0, v[12:13]
	v_mad_i64_i32 v[12:13], s[34:35], v33, s3, 0
	v_or_b32_e32 v32, 5, v20
	v_cndmask_b32_e64 v13, 0, v13, s[54:55]
	v_cndmask_b32_e64 v12, 0, v12, s[54:55]
	v_lshl_add_u64 v[46:47], v[2:3], 0, v[12:13]
	v_mad_i64_i32 v[12:13], s[34:35], v32, s3, 0
	v_cmp_lt_i32_e64 s[56:57], s1, v32
	v_or_b32_e32 v31, 6, v20
	v_cmp_lt_i32_e64 s[58:59], s1, v31
	v_cndmask_b32_e64 v13, 0, v13, s[56:57]
	v_cndmask_b32_e64 v12, 0, v12, s[56:57]
	v_lshl_add_u64 v[48:49], v[2:3], 0, v[12:13]
	v_mad_i64_i32 v[12:13], s[34:35], v31, s3, 0
	v_or_b32_e32 v29, 7, v20
	v_cndmask_b32_e64 v13, 0, v13, s[58:59]
	v_cndmask_b32_e64 v12, 0, v12, s[58:59]
	v_lshl_add_u64 v[70:71], v[2:3], 0, v[12:13]
	v_mad_i64_i32 v[12:13], s[34:35], v29, s3, 0
	v_cmp_lt_i32_e64 s[60:61], s1, v29
	v_or_b32_e32 v30, 9, v20
	v_cmp_lt_i32_e64 s[62:63], s1, v30
	v_cndmask_b32_e64 v13, 0, v13, s[60:61]
	v_cndmask_b32_e64 v12, 0, v12, s[60:61]
	v_lshl_add_u64 v[72:73], v[2:3], 0, v[12:13]
	v_mad_i64_i32 v[12:13], s[34:35], v30, s3, 0
	v_or_b32_e32 v28, 10, v20
	v_cndmask_b32_e64 v13, 0, v13, s[62:63]
	v_cndmask_b32_e64 v12, 0, v12, s[62:63]
	v_lshl_add_u64 v[74:75], v[2:3], 0, v[12:13]
	v_mad_i64_i32 v[12:13], s[34:35], v28, s3, 0
	v_cmp_lt_i32_e64 s[64:65], s1, v28
	v_or_b32_e32 v26, 11, v20
	v_cmp_lt_i32_e64 s[68:69], s1, v26
	v_cndmask_b32_e64 v13, 0, v13, s[64:65]
	v_cndmask_b32_e64 v12, 0, v12, s[64:65]
	v_lshl_add_u64 v[82:83], v[2:3], 0, v[12:13]
	v_mad_i64_i32 v[12:13], s[34:35], v26, s3, 0
	v_or_b32_e32 v25, 12, v20
	v_cndmask_b32_e64 v13, 0, v13, s[68:69]
	v_cndmask_b32_e64 v12, 0, v12, s[68:69]
	v_lshl_add_u64 v[84:85], v[2:3], 0, v[12:13]
	v_mad_i64_i32 v[12:13], s[34:35], v25, s3, 0
	v_cmp_lt_i32_e64 s[70:71], s1, v25
	v_or_b32_e32 v24, 13, v20
	v_add_u32_e32 v0, -1, v20
	v_cndmask_b32_e64 v13, 0, v13, s[70:71]
	v_cndmask_b32_e64 v12, 0, v12, s[70:71]
	v_cndmask_b32_e64 v11, 0, v11, s[46:47]
	v_cndmask_b32_e64 v10, 0, v10, s[46:47]
	v_lshl_add_u64 v[86:87], v[2:3], 0, v[12:13]
	v_mad_i64_i32 v[12:13], s[34:35], v24, s3, 0
	v_cmp_lt_i32_e64 s[72:73], s1, v24
	v_lshl_add_u64 v[52:53], v[2:3], 0, v[10:11]
	v_mad_i64_i32 v[10:11], s[34:35], v0, s3, 0
	v_cmp_lt_i32_e64 s[48:49], s1, v0
	v_or_b32_e32 v22, 14, v20
	v_cndmask_b32_e64 v13, 0, v13, s[72:73]
	v_cndmask_b32_e64 v12, 0, v12, s[72:73]
	v_cndmask_b32_e64 v11, 0, v11, s[48:49]
	v_cndmask_b32_e64 v10, 0, v10, s[48:49]
	v_lshl_add_u64 v[88:89], v[2:3], 0, v[12:13]
	v_mad_i64_i32 v[12:13], s[34:35], v22, s3, 0
	v_cmp_lt_i32_e64 s[74:75], s1, v22
	v_or_b32_e32 v4, 1, v20
	v_or_b32_e32 v34, 2, v20
	v_or_b32_e32 v27, 8, v20
	v_or_b32_e32 v21, 15, v39
	v_lshl_add_u64 v[56:57], v[2:3], 0, v[10:11]
	v_mad_i64_i32 v[10:11], s[34:35], v20, s3, 0
	v_cmp_lt_i32_e64 s[50:51], s1, v20
	v_cndmask_b32_e64 v13, 0, v13, s[74:75]
	v_cndmask_b32_e64 v12, 0, v12, s[74:75]
	v_mad_i64_i32 v[4:5], s[34:35], v4, s3, 0
	v_cmp_gt_i32_e64 s[38:39], s1, v20
	v_mad_i64_i32 v[6:7], s[34:35], v34, s3, 0
	v_cmp_lt_i32_e64 s[42:43], s1, v34
	v_cmp_lt_i32_e64 s[40:41], s1, v27
	v_cndmask_b32_e64 v11, 0, v11, s[50:51]
	v_cndmask_b32_e64 v10, 0, v10, s[50:51]
	v_lshl_add_u64 v[90:91], v[2:3], 0, v[12:13]
	v_mad_i64_i32 v[12:13], s[34:35], v21, s3, 0
	v_cmp_lt_i32_e64 s[66:67], s1, v21
	v_cndmask_b32_e64 v5, v5, 0, s[38:39]
	v_cndmask_b32_e64 v4, v4, 0, s[38:39]
	v_cndmask_b32_e64 v7, 0, v7, s[42:43]
	v_cndmask_b32_e64 v6, 0, v6, s[42:43]
	v_cndmask_b32_e64 v8, 0, v27, s[40:41]
	v_lshl_add_u64 v[10:11], v[2:3], 0, v[10:11]
	v_cndmask_b32_e64 v13, 0, v13, s[66:67]
	v_cndmask_b32_e64 v12, 0, v12, s[66:67]
	v_lshl_add_u64 v[4:5], v[2:3], 0, v[4:5]
	v_lshl_add_u64 v[6:7], v[2:3], 0, v[6:7]
	v_mad_i64_i32 v[8:9], s[34:35], v8, s3, v[2:3]
	v_lshl_add_u64 v[92:93], v[2:3], 0, v[12:13]
	global_load_ushort v2, v[10:11], off
	global_load_ushort v14, v[56:57], off offset:1024
	global_load_ushort v15, v[10:11], off offset:1024
	global_load_ushort v3, v[16:17], off
	global_load_ushort v12, v[16:17], off offset:1024
	global_load_ushort v23, v[16:17], off offset:2048
	global_load_ushort v40, v[10:11], off offset:2048
	global_load_ushort v41, v[56:57], off offset:2048
	s_nop 0
	global_load_ushort v10, v[4:5], off
	global_load_ushort v11, v[6:7], off
	global_load_ushort v36, v[8:9], off
	global_load_ushort v17, v[4:5], off offset:1024
	global_load_ushort v65, v[6:7], off offset:1024
	global_load_ushort v13, v[8:9], off offset:1024
	global_load_ushort v42, v[6:7], off offset:2048
; DI float bf2f(bf16_t b) { return __uint_as_float(((unsigned)b) << 16); }
;     ...
;           for (int e = 0; e < 19; ++e) { const int ti = tt0 + e - 3; const bool ok = (s0 + ti >= 0); const float vv = bf2f(src[(long)(ok ? ti : 0) * PLD]); xr[part][e] = ok ? vv : 0.f; } } }
;     __syncthreads();
;     if (tid < 64) {
;         const float al = a.small[(size_t)(t0 + tid) * 16 + h], bl = a.small[(size_t)(t0 + tid) * 16 + 4 + h];
;         const float xx = al + a.dtb[h]; const float sp = xx > 20.f ? xx : log1pf(__expf(xx));
	global_load_ushort v44, v[4:5], off offset:2048
	global_load_ushort v37, v[46:47], off
	global_load_ushort v55, v[48:49], off
	global_load_ushort v59, v[70:71], off
	global_load_ushort v66, v[46:47], off offset:1024
	global_load_ushort v67, v[48:49], off offset:1024
	global_load_ushort v68, v[70:71], off offset:1024
	global_load_ushort v45, v[48:49], off offset:2048
	s_nop 0
	global_load_ushort v47, v[46:47], off offset:2048
	s_nop 0
	global_load_ushort v60, v[72:73], off
	global_load_ushort v69, v[72:73], off offset:1024
	global_load_ushort v61, v[74:75], off
	global_load_ushort v62, v[82:83], off
	global_load_ushort v16, v[74:75], off offset:1024
	global_load_ushort v46, v[74:75], off offset:2048
	global_load_ushort v48, v[72:73], off offset:2048
	global_load_ushort v49, v[70:71], off offset:2048
	global_load_ushort v78, v[50:51], off
	global_load_ushort v79, v[52:53], off
	global_load_ushort v76, v[50:51], off offset:1024
	global_load_ushort v77, v[52:53], off offset:1024
	global_load_ushort v80, v[56:57], off
	s_nop 0
	global_load_ushort v57, v[52:53], off offset:2048
	global_load_ushort v58, v[50:51], off offset:2048
	s_nop 0
	global_load_ushort v50, v[8:9], off offset:2048
	global_load_ushort v72, v[82:83], off offset:1024
	global_load_ushort v63, v[84:85], off
	global_load_ushort v64, v[86:87], off
	global_load_ushort v70, v[84:85], off offset:1024
	global_load_ushort v71, v[86:87], off offset:1024
	global_load_ushort v51, v[86:87], off offset:2048
	global_load_ushort v52, v[84:85], off offset:2048
	global_load_ushort v53, v[82:83], off offset:2048
	global_load_ushort v81, v[88:89], off
	s_nop 0
	global_load_ushort v82, v[90:91], off
	global_load_ushort v83, v[92:93], off
	global_load_ushort v74, v[88:89], off offset:1024
	global_load_ushort v75, v[90:91], off offset:1024
	global_load_ushort v73, v[92:93], off offset:1024
	global_load_ushort v54, v[90:91], off offset:2048
	global_load_ushort v56, v[88:89], off offset:2048
	global_load_ushort v43, v[92:93], off offset:2048
	v_and_b32_e32 v18, 63, v38
	v_cmp_gt_i32_e32 vcc, 64, v38
	s_barrier
	s_and_saveexec_b64 s[78:79], vcc
	s_cbranch_execz .LBB0_401
	v_add_u32_e32 v4, s0, v38
	v_ashrrev_i32_e32 v5, 31, v4
	v_readlane_b32 s0, v252, 16
	v_lshlrev_b64 v[4:5], 6, v[4:5]
	v_readlane_b32 s1, v252, 17
	s_lshl_b32 s4, s13, 2
	s_nop 0
	v_lshl_add_u64 v[4:5], s[0:1], 0, v[4:5]
	v_lshl_add_u64 v[4:5], v[4:5], 0, s[4:5]
	v_readlane_b32 s0, v255, 11
	global_load_dword v6, v[4:5], off
	global_load_dword v0, v[4:5], off offset:16
	v_mov_b32_e32 v4, s4
	v_readlane_b32 s1, v255, 12
	s_nop 4
	global_load_dword v4, v4, s[0:1]
	v_readlane_b32 s98, v255, 9
	v_readlane_b32 s99, v255, 10
	v_mov_b32_e32 v93, s4
	s_nop 4
	global_load_dword v93, v93, s[98:99]
	s_mov_b32 s0, 0x41a00000
	s_waitcnt vmcnt(0)
	v_add_f32_e32 v4, v6, v4
	v_cmp_nlt_f32_e64 s[0:1], s0, v4
	s_and_saveexec_b64 s[80:81], s[0:1]
	s_cbranch_execz .LBB0_400
	v_mul_f32_e32 v4, 0x3fb8aa3b, v4
	v_exp_f32_e32 v92, v4
	s_mov_b32 s0, 0x3f2aaaab
	v_add_f32_e32 v6, 1.0, v92
	v_frexp_mant_f32_e32 v8, v6
	v_cvt_f64_f32_e32 v[4:5], v6
	v_frexp_exp_i32_f64_e32 v4, v[4:5]
	v_cmp_gt_f32_e64 s[0:1], s0, v8
	v_add_f32_e32 v7, -1.0, v6
	v_sub_f32_e32 v9, v7, v6
	v_subbrev_co_u32_e64 v86, s[0:1], 0, v4, s[0:1]
	v_sub_u32_e32 v4, 0, v86
	v_sub_f32_e32 v7, v92, v7
	v_add_f32_e32 v9, 1.0, v9
	v_ldexp_f32 v5, v6, v4
	v_add_f32_e32 v7, v7, v9
	v_add_f32_e32 v6, -1.0, v5
	v_add_f32_e32 v8, 1.0, v5
	v_ldexp_f32 v4, v7, v4
	v_add_f32_e32 v7, 1.0, v6
	v_add_f32_e32 v9, -1.0, v8
	v_sub_f32_e32 v7, v5, v7
	v_sub_f32_e32 v5, v5, v9
	v_add_f32_e32 v7, v4, v7
	v_add_f32_e32 v4, v4, v5
	v_add_f32_e32 v87, v8, v4
	v_rcp_f32_e32 v89, v87
	v_sub_f32_e32 v5, v87, v8
	v_sub_f32_e32 v88, v4, v5
	v_add_f32_e32 v5, v6, v7
	v_mul_f32_e32 v91, v5, v89
	v_sub_f32_e32 v4, v5, v6
	v_mul_f32_e32 v6, v87, v91
	v_fma_f32 v8, v91, v87, -v6
	v_fmac_f32_e32 v8, v91, v88
	v_sub_f32_e32 v90, v7, v4
	v_add_f32_e32 v4, v6, v8
	v_sub_f32_e32 v7, v5, v4
	v_pk_add_f32 v[84:85], v[4:5], v[6:7] neg_lo:[0,1] neg_hi:[0,1]
	v_mov_b32_e32 v9, v4
	v_pk_add_f32 v[4:5], v[84:85], v[8:9] neg_lo:[0,1] neg_hi:[0,1]
	s_mov_b32 s0, 0x3f317218
	v_add_f32_e32 v5, v90, v5
	v_add_f32_e32 v4, v4, v5
	v_add_f32_e32 v5, v7, v4
	v_mul_f32_e32 v90, v89, v5
	v_mul_f32_e32 v6, v87, v90
	v_fma_f32 v8, v90, v87, -v6
	v_fmac_f32_e32 v8, v90, v88
	v_sub_f32_e32 v7, v7, v5
	v_add_f32_e32 v87, v4, v7
	v_add_f32_e32 v4, v6, v8
	v_sub_f32_e32 v7, v5, v4
	v_pk_add_f32 v[84:85], v[4:5], v[6:7] neg_lo:[0,1] neg_hi:[0,1]
	v_mov_b32_e32 v9, v4
	v_pk_add_f32 v[4:5], v[84:85], v[8:9] neg_lo:[0,1] neg_hi:[0,1]
	s_nop 0
	v_add_f32_e32 v5, v87, v5
	v_add_f32_e32 v4, v4, v5
	v_add_f32_e32 v5, v91, v90
	v_add_f32_e32 v4, v7, v4
	v_sub_f32_e32 v6, v5, v91
	v_mul_f32_e32 v4, v89, v4
	v_sub_f32_e32 v6, v90, v6
	v_add_f32_e32 v6, v6, v4
	v_add_f32_e32 v8, v5, v6
	v_mul_f32_e32 v9, v8, v8
	v_mov_b32_e32 v4, 0x3ecc95a3
	v_fmamk_f32 v4, v9, 0x3e9b6dac, v4
	v_fmaak_f32 v247, v9, v4, 0x3f2aaada
	v_cvt_f32_i32_e32 v4, v86
	v_sub_f32_e32 v5, v8, v5
	v_sub_f32_e32 v5, v6, v5
	v_ldexp_f32 v84, v5, 1
	v_mul_f32_e32 v5, v8, v9
	v_ldexp_f32 v7, v8, 1
	v_pk_mul_f32 v[8:9], v[4:5], v[246:247]
	s_nop 0
	v_fma_f32 v6, v4, s0, -v8
	v_fmac_f32_e32 v6, 0xb102e308, v4
	v_pk_add_f32 v[4:5], v[8:9], v[6:7]
	s_mov_b32 s0, 0x7f800000
	v_sub_f32_e32 v7, v5, v7
	v_sub_f32_e32 v7, v9, v7
	v_add_f32_e32 v85, v84, v7
	v_mov_b32_e32 v84, v8
	v_pk_add_f32 v[8:9], v[4:5], v[8:9] neg_lo:[0,1] neg_hi:[0,1]
	v_pk_add_f32 v[86:87], v[4:5], v[84:85]
	v_mov_b32_e32 v7, v4
	v_mov_b32_e32 v9, v87
	v_pk_add_f32 v[88:89], v[6:7], v[8:9] neg_lo:[0,1] neg_hi:[0,1]
	v_pk_add_f32 v[6:7], v[6:7], v[8:9]
	v_mov_b32_e32 v84, v85
	v_pk_add_f32 v[8:9], v[6:7], v[4:5] op_sel:[1,0] op_sel_hi:[0,1] neg_lo:[0,1] neg_hi:[0,1]
	v_pk_add_f32 v[90:91], v[86:87], v[8:9] op_sel_hi:[1,0] neg_lo:[0,1] neg_hi:[0,1]
	v_mov_b32_e32 v86, v87
	v_mov_b32_e32 v87, v7
	v_pk_mov_b32 v[8:9], v[4:5], v[8:9] op_sel:[1,0]
	v_mov_b32_e32 v85, v4
	v_pk_add_f32 v[8:9], v[86:87], v[8:9] neg_lo:[0,1] neg_hi:[0,1]
	v_mov_b32_e32 v90, v88
	v_pk_add_f32 v[4:5], v[84:85], v[8:9] neg_lo:[0,1] neg_hi:[0,1]
	v_mov_b32_e32 v89, v7
	v_pk_add_f32 v[8:9], v[90:91], v[4:5]
	v_cmp_neq_f32_e64 s[0:1], s0, v92
	v_pk_add_f32 v[84:85], v[8:9], v[8:9] op_sel:[0,1] op_sel_hi:[1,0]
	s_nop 0
	v_pk_add_f32 v[6:7], v[6:7], v[84:85] op_sel:[1,0] op_sel_hi:[0,1]
	v_mov_b32_e32 v9, v6
	v_pk_add_f32 v[86:87], v[8:9], v[88:89] neg_lo:[0,1] neg_hi:[0,1]
	v_mov_b32_e32 v5, v84
	v_sub_f32_e32 v7, v8, v86
	v_pk_add_f32 v[4:5], v[4:5], v[86:87] neg_lo:[0,1] neg_hi:[0,1]
	v_sub_f32_e32 v7, v88, v7
	v_add_f32_e32 v4, v4, v7
	v_add_f32_e32 v4, v4, v5
	v_add_f32_e32 v4, v6, v4
	v_cndmask_b32_e64 v4, v248, v4, s[0:1]
	v_cmp_ngt_f32_e64 s[0:1], -1.0, v92
	s_nop 1
	v_cndmask_b32_e64 v4, v224, v4, s[0:1]
	v_cmp_neq_f32_e64 s[0:1], -1.0, v92
	s_nop 1
	v_cndmask_b32_e64 v4, v219, v4, s[0:1]
	s_mov_b32 s0, 0x33800000
	v_cmp_lt_f32_e64 s[0:1], |v92|, s0
	s_nop 1
	v_cndmask_b32_e64 v4, v4, v92, s[0:1]
; DI float sigmoidf_(float x) { return __builtin_amdgcn_rcpf(1.f + __builtin_amdgcn_exp2f(-LOG2E * x)); }
;     ...
;         float g = -__expf(a.alog[h]) * sp;
;         for (int o = 1; o < 64; o <<= 1) { const float t = __shfl_up(g, o); if (lane >= o) g += t; }
;         gcs[tid] = g; betas[tid] = sigmoidf_(bl); egs[tid] = __expf(g);
.LBB0_400:
	s_or_b64 exec, exec, s[80:81]
	v_readlane_b32 s0, v255, 9
	v_mov_b32_e32 v5, s4
	v_readlane_b32 s1, v255, 10
	v_and_b32_e32 v7, 64, v218
	v_add_u32_e32 v8, -1, v218
	v_mul_f32_e32 v0, 0xbfb8aa3b, v0
	v_exp_f32_e32 v0, v0
	s_nop 0
	v_cmp_lt_i32_e64 s[0:1], v8, v7
	v_add_f32_e32 v0, 1.0, v0
	v_rcp_f32_e32 v0, v0
	v_cndmask_b32_e64 v8, v8, v218, s[0:1]
	v_lshlrev_b32_e32 v8, 2, v8
	v_cmp_eq_u32_e64 s[0:1], 0, v18
	s_waitcnt vmcnt(0)
	v_mul_f32_e32 v5, 0x3fb8aa3b, v93
	v_exp_f32_e32 v5, v5
	s_nop 0
	v_mul_f32_e64 v6, v4, -v5
	ds_bpermute_b32 v8, v8, v6
	s_waitcnt lgkmcnt(0)
	v_fma_f32 v4, v4, -v5, v8
	v_add_u32_e32 v5, -2, v218
	v_cndmask_b32_e64 v4, v4, v6, s[0:1]
	v_cmp_lt_i32_e64 s[0:1], v5, v7
	s_nop 1
	v_cndmask_b32_e64 v5, v5, v218, s[0:1]
	v_lshlrev_b32_e32 v5, 2, v5
	ds_bpermute_b32 v5, v5, v4
	v_cmp_gt_u32_e64 s[0:1], 2, v18
	s_waitcnt lgkmcnt(0)
	v_add_f32_e32 v5, v4, v5
	v_cndmask_b32_e64 v4, v5, v4, s[0:1]
	v_add_u32_e32 v5, -4, v218
	v_cmp_lt_i32_e64 s[0:1], v5, v7
	s_nop 1
	v_cndmask_b32_e64 v5, v5, v218, s[0:1]
	v_lshlrev_b32_e32 v5, 2, v5
	ds_bpermute_b32 v5, v5, v4
	v_cmp_gt_u32_e64 s[0:1], 4, v18
	s_waitcnt lgkmcnt(0)
	v_add_f32_e32 v5, v4, v5
	v_cndmask_b32_e64 v4, v5, v4, s[0:1]
	v_add_u32_e32 v5, -8, v218
	v_cmp_lt_i32_e64 s[0:1], v5, v7
	s_nop 1
	v_cndmask_b32_e64 v5, v5, v218, s[0:1]
	v_lshlrev_b32_e32 v5, 2, v5
	ds_bpermute_b32 v5, v5, v4
	v_cmp_gt_u32_e64 s[0:1], 8, v18
	s_waitcnt lgkmcnt(0)
	v_add_f32_e32 v5, v4, v5
	v_cndmask_b32_e64 v4, v5, v4, s[0:1]
	v_add_u32_e32 v5, -16, v218
	v_cmp_lt_i32_e64 s[0:1], v5, v7
	s_nop 1
	v_cndmask_b32_e64 v5, v5, v218, s[0:1]
	v_lshlrev_b32_e32 v5, 2, v5
	ds_bpermute_b32 v5, v5, v4
	v_cmp_gt_u32_e64 s[0:1], 16, v18
	s_waitcnt lgkmcnt(0)
	v_add_f32_e32 v5, v4, v5
	v_cndmask_b32_e64 v4, v5, v4, s[0:1]
	v_subrev_u32_e32 v5, 32, v218
	v_cmp_lt_i32_e64 s[0:1], v5, v7
	s_nop 1
	v_cndmask_b32_e64 v5, v5, v218, s[0:1]
	v_lshlrev_b32_e32 v5, 2, v5
	ds_bpermute_b32 v5, v5, v4
	v_cmp_gt_u32_e64 s[0:1], 32, v18
	s_waitcnt lgkmcnt(0)
	v_add_f32_e32 v5, v4, v5
	v_cndmask_b32_e64 v4, v5, v4, s[0:1]
	v_lshl_add_u32 v5, v38, 2, 0
	v_add_u32_e32 v6, 0x25480, v5
	ds_write_b32 v6, v4
	v_add_u32_e32 v6, 0x25580, v5
	ds_write_b32 v6, v0
	v_mul_f32_e32 v0, 0x3fb8aa3b, v4
	v_exp_f32_e32 v0, v0
	v_add_u32_e32 v4, 0x25680, v5
	ds_write_b32 v4, v0
